# cand2 + A1 (HGRN2 chunk-state) loop: counted vmcnt at the loop top so the previous unit's 8 state stores stay in flight
# speedup vs baseline: 1.0045x; 1.0027x over previous
; #define GAS __attribute__((address_space(1)))
; template <bool WANT_Q> __device__ __forceinline__ void hg_issue(Frame& F, HgRegs& R, int u) {
;     const int bh = u >> 7, c = u & 127, b = bh >> 3, h = bh & 7, dp = F.tid & 63, grp = F.tid >> 6;
;     const bf16* P = F_P16 + (size_t)(b * SEQ + 64 * c) * P16S + h * HD;
; #pragma unroll
;     for (int j = 0; j < 8; ++j) { const bf16* src = P + (size_t)(8 * grp + j) * P16S + 2 * dp;
;         R.lf[j] = *(const GAS unsigned*)(src + 1024); if (WANT_Q) R.q[j] = *(const GAS unsigned*)(src); }
; #pragma unroll
;     for (int i = 0; i < 2; ++i) { const int ch = F.tid + 512 * i, r = ch >> 4, cc = ch & 15; R.v[i] = *(const GAS v4u*)(P + (size_t)r * P16S + 2048 + cc * 8); }
; }
; __device__ __forceinline__ void hgrn2_a1_all(Frame& F) {
;     constexpr int SET = 64 * VR * 2 + 8 * 128 * 2;
;     const int dp = F.tid & 63, grp = F.tid >> 6, g = F.lane >> 4, li = F.lane & 15;
;     HgRegs R; int u = F.vcu, par = 0;
;     if (u < HG_UNITS) hg_issue<false>(F, R, u);
.LBB0_330:
	s_waitcnt vmcnt(0)
	v_lshlrev_b32_e32 v2, 3, v18
	s_waitcnt lgkmcnt(0)
	v_lshrrev_b32_e32 v3, 1, v18
	v_and_b32_e32 v1, 63, v18
	s_ashr_i32 s8, s2, 6
	s_andn2_b64 vcc, exec, s[0:1]
	v_and_b32_e32 v183, 15, v18
	v_and_b32_e32 v22, 0x78, v2
	v_and_b32_e32 v20, 24, v3
	s_cbranch_vccnz .LBB0_338
	s_lshl_b32 s0, s54, 3
	s_lshl_b32 s1, s54, 6
	s_and_b32 s0, s0, 0xffffe000
	s_and_b32 s1, s1, 0x1fc0
	s_or_b32 s0, s0, s1
	s_ashr_i32 s1, s0, 31
	s_and_b32 s2, s54, 0x380
	s_lshl_b64 s[0:1], s[0:1], 14
	s_add_u32 s0, s74, s0
	v_ashrrev_i32_e32 v19, 3, v18
	s_addc_u32 s1, s75, s1
	s_lshl_b32 s2, s2, 1
	v_and_b32_e32 v2, -8, v19
	v_lshlrev_b32_e32 v3, 1, v18
	s_add_u32 s0, s0, s2
	v_and_b32_e32 v26, 0x7e, v3
	v_ashrrev_i32_e32 v3, 31, v2
	s_addc_u32 s1, s1, 0
	v_lshlrev_b32_e32 v162, 1, v26
	v_lshlrev_b64 v[28:29], 14, v[2:3]
	v_or_b32_e32 v8, 1, v2
	v_or_b32_e32 v10, 2, v2
	v_or_b32_e32 v12, 3, v2
	v_or_b32_e32 v14, 4, v2
	v_or_b32_e32 v16, 5, v2
	v_or_b32_e32 v2, 6, v2
	v_or_b32_e32 v42, 7, v19
	v_lshl_add_u64 v[4:5], s[0:1], 0, v[162:163]
	v_ashrrev_i32_e32 v9, 31, v8
	s_waitcnt lgkmcnt(0)
	v_ashrrev_i32_e32 v11, 31, v10
	v_ashrrev_i32_e32 v13, 31, v12
	v_ashrrev_i32_e32 v15, 31, v14
	v_ashrrev_i32_e32 v17, 31, v16
	v_ashrrev_i32_e32 v3, 31, v2
	v_ashrrev_i32_e32 v43, 31, v42
	v_lshl_add_u64 v[6:7], v[4:5], 0, v[28:29]
	v_lshlrev_b64 v[30:31], 14, v[8:9]
	v_lshlrev_b64 v[32:33], 14, v[10:11]
	v_lshlrev_b64 v[34:35], 14, v[12:13]
	v_lshlrev_b64 v[36:37], 14, v[14:15]
	v_lshlrev_b64 v[38:39], 14, v[16:17]
	v_lshlrev_b64 v[40:41], 14, v[2:3]
	v_lshlrev_b64 v[42:43], 14, v[42:43]
	v_lshl_add_u64 v[8:9], v[4:5], 0, v[30:31]
	v_lshl_add_u64 v[10:11], v[4:5], 0, v[32:33]
	v_lshl_add_u64 v[12:13], v[4:5], 0, v[34:35]
	v_lshl_add_u64 v[14:15], v[4:5], 0, v[36:37]
	v_lshl_add_u64 v[16:17], v[4:5], 0, v[38:39]
	v_lshl_add_u64 v[2:3], v[4:5], 0, v[40:41]
	v_lshl_add_u64 v[4:5], v[4:5], 0, v[42:43]
	global_load_dword v19, v[6:7], off offset:2048
	global_load_dword v21, v[8:9], off offset:2048
	global_load_dword v23, v[10:11], off offset:2048
	global_load_dword v27, v[12:13], off offset:2048
	global_load_dword v82, v[14:15], off offset:2048
	global_load_dword v83, v[16:17], off offset:2048
	global_load_dword v85, v[2:3], off offset:2048
	global_load_dword v89, v[4:5], off offset:2048
	v_ashrrev_i32_e32 v25, 31, v24
	v_add_u32_e32 v6, 0x200, v18
	v_lshlrev_b64 v[44:45], 14, v[24:25]
	v_ashrrev_i32_e32 v10, 4, v6
	v_lshl_add_u64 v[2:3], s[0:1], 0, v[44:45]
	v_lshlrev_b32_e32 v4, 1, v22
	v_mov_b32_e32 v5, v163
	v_ashrrev_i32_e32 v11, 31, v10
	v_lshl_add_u64 v[2:3], v[2:3], 0, v[4:5]
	s_movk_i32 s2, 0x1000
	v_lshlrev_b64 v[46:47], 14, v[10:11]
	v_add_co_u32_e32 v2, vcc, s2, v2
	v_lshl_add_u64 v[6:7], s[0:1], 0, v[46:47]
	s_nop 0
	v_addc_co_u32_e32 v3, vcc, 0, v3, vcc
	v_lshl_add_u64 v[4:5], v[6:7], 0, v[4:5]
	v_add_co_u32_e32 v6, vcc, s2, v4
	v_ashrrev_i32_e32 v11, 6, v18
	s_nop 0
	v_addc_co_u32_e32 v7, vcc, 0, v5, vcc
	global_load_dwordx4 v[2:5], v[2:3], off
	s_nop 0
	global_load_dwordx4 v[6:9], v[6:7], off
	s_movk_i32 s4, 0x900
	v_mul_lo_u32 v84, v11, s4
	s_movk_i32 s4, 0x120
	v_mul_lo_u32 v86, v24, s4
	v_mul_lo_u32 v87, v10, s4
	s_lshl_b32 s4, s8, 4
	s_ashr_i32 s55, s54, 31
	s_lshl_b32 s7, s8, 5
	s_ashr_i32 s5, s4, 31
	s_lshl_b64 s[10:11], s[54:55], 9
	s_add_u32 s9, s10, 0x40d00000
	s_addc_u32 s10, s11, 0
	v_mov_b32_e32 v49, s10
	s_lshl_b64 s[10:11], s[54:55], 15
	v_lshlrev_b32_e32 v10, 8, v183
	v_lshlrev_b32_e32 v25, 9, v11
	v_bfe_u32 v12, v18, 2, 4
	v_lshlrev_b32_e32 v13, 2, v1
	v_cmp_lt_i32_e64 s[0:1], 0, v11
	v_cmp_lt_i32_e64 s[2:3], 1, v11
	v_cmp_lt_i32_e64 s[42:43], 2, v11
	v_cmp_lt_i32_e64 s[44:45], 3, v11
	v_cmp_lt_i32_e64 s[46:47], 4, v11
	v_cmp_lt_i32_e64 s[48:49], 5, v11
	v_cmp_lt_i32_e64 s[50:51], 6, v11
	v_cmp_lt_i32_e64 s[52:53], 7, v11
	v_or3_b32 v10, s10, v10, v20
	v_mov_b32_e32 v11, s11
	v_mul_u32_u24_e32 v12, 0x90, v12
	v_and_b32_e32 v13, 12, v13
	v_lshl_add_u64 v[50:51], s[4:5], 1, v[10:11]
	s_add_i32 s4, s76, s54
	s_mov_b32 s6, 0
	v_cmp_gt_u32_e64 s[36:37], 64, v18
	v_sub_u32_e32 v88, 0, v162
	v_lshl_or_b32 v48, v1, 3, s9
	s_lshl_b32 s9, s4, 3
	s_lshl_b32 s10, s4, 6
	v_lshlrev_b32_e32 v90, 1, v12
	v_lshlrev_b32_e32 v91, 1, v13
	s_mov_b32 s11, s54
	s_waitcnt vmcnt(0)
	s_branch .LBB0_333

; #define LAS __attribute__((address_space(3)))
; #define LDS_BARRIER() do { asm volatile("s_waitcnt lgkmcnt(0)" ::: "memory"); __builtin_amdgcn_s_barrier(); asm volatile("" ::: "memory"); } while (0)
; __device__ __forceinline__ f32x2 h2v(unsigned w) { return (f32x2){h2f((unsigned short)(w & 0xffffu)), h2f((unsigned short)(w >> 16))}; }
; __device__ __forceinline__ void hgrn2_a1_all(Frame& F) {
;     ...
;         LAS unsigned short* Lk = (LAS unsigned short*)(F.lds) + par * SET;
;         LAS unsigned short* Lv = Lk + 64 * VR;
;         LAS float* Ltot = (LAS float*)(Lv + 64 * VR);
;         f32x2 bl[8]; { f32x2 r = {0.f, 0.f};
; #pragma unroll
;             for (int j = 0; j < 8; ++j) { r += h2v(R.lf[j]); bl[j] = r; }
;             *(LAS f32x2*)(Ltot + grp * 128 + 2 * dp) = r; }
; #pragma unroll
;         for (int i = 0; i < 2; ++i) { const int ch = F.tid + 512 * i, r = ch >> 4, cc = ch & 15; *(LAS v4u*)(Lv + r * VR + cc * 8) = R.v[i]; }
;         LDS_BARRIER();
.LBB0_333:
	s_waitcnt vmcnt(8)
	v_cvt_f32_f16_sdwa v79, v19 dst_sel:DWORD dst_unused:UNUSED_PAD src0_sel:WORD_1
	v_cvt_f32_f16_e32 v78, v19
	v_cvt_f32_f16_sdwa v73, v21 dst_sel:DWORD dst_unused:UNUSED_PAD src0_sel:WORD_1
	v_cvt_f32_f16_e32 v72, v21
	v_cvt_f32_f16_sdwa v69, v23 dst_sel:DWORD dst_unused:UNUSED_PAD src0_sel:WORD_1
	v_cvt_f32_f16_e32 v68, v23
	v_cvt_f32_f16_sdwa v65, v27 dst_sel:DWORD dst_unused:UNUSED_PAD src0_sel:WORD_1
	v_cvt_f32_f16_e32 v64, v27
	v_pk_add_f32 v[74:75], v[78:79], 0 op_sel_hi:[1,0]
	v_cvt_f32_f16_sdwa v61, v82 dst_sel:DWORD dst_unused:UNUSED_PAD src0_sel:WORD_1
	v_cvt_f32_f16_e32 v60, v82
	v_pk_add_f32 v[70:71], v[74:75], v[72:73]
	v_cvt_f32_f16_sdwa v57, v83 dst_sel:DWORD dst_unused:UNUSED_PAD src0_sel:WORD_1
	v_cvt_f32_f16_e32 v56, v83
	v_pk_add_f32 v[66:67], v[70:71], v[68:69]
	v_cvt_f32_f16_sdwa v53, v85 dst_sel:DWORD dst_unused:UNUSED_PAD src0_sel:WORD_1
	v_cvt_f32_f16_e32 v52, v85
	v_pk_add_f32 v[62:63], v[66:67], v[64:65]
	v_cvt_f32_f16_sdwa v13, v89 dst_sel:DWORD dst_unused:UNUSED_PAD src0_sel:WORD_1
	v_cvt_f32_f16_e32 v12, v89
	s_mul_i32 s4, s6, 0xa000
	v_pk_add_f32 v[58:59], v[62:63], v[60:61]
	s_add_i32 s12, s4, 0
	v_pk_add_f32 v[54:55], v[58:59], v[56:57]
	v_lshl_add_u32 v11, v26, 2, s12
	v_pk_add_f32 v[16:17], v[54:55], v[52:53]
	v_add_u32_e32 v10, v11, v25
	v_pk_add_f32 v[14:15], v[16:17], v[12:13]
	ds_write_b64 v10, v[14:15] offset:36864
	v_lshlrev_b32_e32 v10, 1, v22
	v_add3_u32 v76, s12, v86, v10
	ds_write_b128 v76, v[2:5] offset:18432
	v_add3_u32 v76, s12, v87, v10
	ds_write_b128 v76, v[6:9] offset:18432
	s_waitcnt lgkmcnt(0)
	s_barrier
; #define GAS __attribute__((address_space(1)))
; #define LAS __attribute__((address_space(3)))
; __device__ __forceinline__ f32x2 expv(f32x2 v) { const f32x2 t = v * 1.4426950408889634f; return (f32x2){__builtin_amdgcn_exp2f(t.x), __builtin_amdgcn_exp2f(t.y)}; }
; __device__ __forceinline__ f32x2 h2v(unsigned w) { return (f32x2){h2f((unsigned short)(w & 0xffffu)), h2f((unsigned short)(w >> 16))}; }
; __device__ __forceinline__ unsigned pk2v(f32x2 v) { return pk2(v.x, v.y); }
; __device__ __forceinline__ void hgrn2_a1_all(Frame& F) {
;     ...
;         { f32x2 off = {0.f, 0.f}, tot = {0.f, 0.f};
; #pragma unroll
;           for (int gg = 0; gg < 8; ++gg) { const f32x2 t = *(const LAS f32x2*)(Ltot + gg * 128 + 2 * dp); if (gg < grp) off += t; tot += t; }
; #pragma unroll
;           for (int j = 0; j < 8; ++j) { const f32x2 key = 1.0f - expv(h2v(R.lf[j]));
;               *(LAS unsigned*)(Lk + (8 * grp + j) * VR + 2 * dp) = pk2v(key * expv(tot - (bl[j] + off))); }
;           if (grp == 0) *(GAS f32x2*)((float*)(F.ws + WS_DEC) + (size_t)u * 128 + 2 * dp) = expv(tot); }
	ds_read2st64_b64 v[92:95], v11 offset0:72 offset1:73
	s_mov_b32 s4, 0x3fb8aa3b
	v_pk_mul_f32 v[78:79], v[78:79], s[4:5] op_sel_hi:[1,0]
	v_pk_mul_f32 v[72:73], v[72:73], s[4:5] op_sel_hi:[1,0]
	v_pk_mul_f32 v[68:69], v[68:69], s[4:5] op_sel_hi:[1,0]
	s_waitcnt lgkmcnt(0)
	v_pk_add_f32 v[76:77], v[92:93], 0 op_sel_hi:[1,0]
	v_pk_mul_f32 v[64:65], v[64:65], s[4:5] op_sel_hi:[1,0]
	v_cndmask_b32_e64 v81, 0, v77, s[0:1]
	v_cndmask_b32_e64 v80, 0, v76, s[0:1]
	v_pk_add_f32 v[92:93], v[94:95], v[80:81]
	v_pk_add_f32 v[76:77], v[76:77], v[94:95]
	v_cndmask_b32_e64 v81, v81, v93, s[2:3]
	v_cndmask_b32_e64 v80, v80, v92, s[2:3]
	ds_read2st64_b64 v[92:95], v11 offset0:74 offset1:75
	v_exp_f32_e32 v78, v78
	v_exp_f32_e32 v79, v79
	v_exp_f32_e32 v72, v72
	v_exp_f32_e32 v73, v73
	s_waitcnt lgkmcnt(0)
	v_pk_add_f32 v[96:97], v[92:93], v[80:81]
	v_pk_add_f32 v[76:77], v[76:77], v[92:93]
	v_cndmask_b32_e64 v81, v81, v97, s[42:43]
	v_cndmask_b32_e64 v80, v80, v96, s[42:43]
	v_pk_add_f32 v[92:93], v[94:95], v[80:81]
	v_pk_add_f32 v[76:77], v[76:77], v[94:95]
	v_cndmask_b32_e64 v81, v81, v93, s[44:45]
	v_cndmask_b32_e64 v80, v80, v92, s[44:45]
	ds_read2st64_b64 v[92:95], v11 offset0:76 offset1:77
	v_exp_f32_e32 v68, v68
	v_exp_f32_e32 v69, v69
	v_exp_f32_e32 v64, v64
	v_exp_f32_e32 v65, v65
	s_waitcnt lgkmcnt(0)
	v_pk_add_f32 v[96:97], v[92:93], v[80:81]
	v_pk_add_f32 v[76:77], v[76:77], v[92:93]
	v_cndmask_b32_e64 v81, v81, v97, s[46:47]
	v_cndmask_b32_e64 v80, v80, v96, s[46:47]
	v_pk_add_f32 v[92:93], v[94:95], v[80:81]
	v_pk_add_f32 v[76:77], v[76:77], v[94:95]
	v_cndmask_b32_e64 v81, v81, v93, s[48:49]
	v_cndmask_b32_e64 v80, v80, v92, s[48:49]
	ds_read2st64_b64 v[92:95], v11 offset0:78 offset1:79
	v_pk_mul_f32 v[60:61], v[60:61], s[4:5] op_sel_hi:[1,0]
	v_pk_mul_f32 v[56:57], v[56:57], s[4:5] op_sel_hi:[1,0]
	v_pk_mul_f32 v[52:53], v[52:53], s[4:5] op_sel_hi:[1,0]
	v_pk_mul_f32 v[12:13], v[12:13], s[4:5] op_sel_hi:[1,0]
	s_waitcnt lgkmcnt(0)
	v_pk_add_f32 v[96:97], v[92:93], v[80:81]
	v_pk_add_f32 v[76:77], v[76:77], v[92:93]
	v_cndmask_b32_e64 v81, v81, v97, s[50:51]
	v_cndmask_b32_e64 v80, v80, v96, s[50:51]
	v_pk_add_f32 v[92:93], v[94:95], v[80:81]
	v_pk_add_f32 v[76:77], v[76:77], v[94:95]
	v_cndmask_b32_e64 v81, v81, v93, s[52:53]
	v_cndmask_b32_e64 v80, v80, v92, s[52:53]
	v_pk_add_f32 v[74:75], v[74:75], v[80:81]
	v_pk_add_f32 v[70:71], v[70:71], v[80:81]
	v_pk_add_f32 v[66:67], v[66:67], v[80:81]
	v_pk_add_f32 v[62:63], v[62:63], v[80:81]
	v_pk_add_f32 v[74:75], v[76:77], v[74:75] neg_lo:[0,1] neg_hi:[0,1]
	v_pk_add_f32 v[70:71], v[76:77], v[70:71] neg_lo:[0,1] neg_hi:[0,1]
	v_pk_add_f32 v[66:67], v[76:77], v[66:67] neg_lo:[0,1] neg_hi:[0,1]
	v_pk_add_f32 v[62:63], v[76:77], v[62:63] neg_lo:[0,1] neg_hi:[0,1]
	v_pk_add_f32 v[58:59], v[58:59], v[80:81]
	v_pk_add_f32 v[54:55], v[54:55], v[80:81]
	v_pk_add_f32 v[16:17], v[16:17], v[80:81]
	v_pk_add_f32 v[14:15], v[14:15], v[80:81]
	v_pk_mul_f32 v[74:75], v[74:75], s[4:5] op_sel_hi:[1,0]
	v_pk_mul_f32 v[70:71], v[70:71], s[4:5] op_sel_hi:[1,0]
	v_pk_mul_f32 v[66:67], v[66:67], s[4:5] op_sel_hi:[1,0]
	v_pk_mul_f32 v[62:63], v[62:63], s[4:5] op_sel_hi:[1,0]
	v_pk_add_f32 v[58:59], v[76:77], v[58:59] neg_lo:[0,1] neg_hi:[0,1]
	v_pk_add_f32 v[54:55], v[76:77], v[54:55] neg_lo:[0,1] neg_hi:[0,1]
	v_pk_add_f32 v[16:17], v[76:77], v[16:17] neg_lo:[0,1] neg_hi:[0,1]
	v_pk_add_f32 v[14:15], v[76:77], v[14:15] neg_lo:[0,1] neg_hi:[0,1]
	v_exp_f32_e32 v74, v74
	v_exp_f32_e32 v75, v75
	v_exp_f32_e32 v70, v70
	v_exp_f32_e32 v71, v71
	v_exp_f32_e32 v66, v66
	v_exp_f32_e32 v67, v67
	v_exp_f32_e32 v62, v62
	v_exp_f32_e32 v63, v63
	v_exp_f32_e32 v60, v60
	v_exp_f32_e32 v61, v61
	v_pk_mul_f32 v[58:59], v[58:59], s[4:5] op_sel_hi:[1,0]
	v_exp_f32_e32 v56, v56
	v_exp_f32_e32 v57, v57
	v_pk_mul_f32 v[54:55], v[54:55], s[4:5] op_sel_hi:[1,0]
	v_exp_f32_e32 v52, v52
	v_exp_f32_e32 v53, v53
	v_pk_mul_f32 v[16:17], v[16:17], s[4:5] op_sel_hi:[1,0]
	v_exp_f32_e32 v12, v12
	v_exp_f32_e32 v13, v13
	v_pk_mul_f32 v[14:15], v[14:15], s[4:5] op_sel_hi:[1,0]
	v_exp_f32_e32 v58, v58
	v_exp_f32_e32 v59, v59
	v_exp_f32_e32 v54, v54
	v_exp_f32_e32 v55, v55
	v_exp_f32_e32 v16, v16
	v_exp_f32_e32 v17, v17
	v_exp_f32_e32 v14, v14
	v_exp_f32_e32 v15, v15
	v_pk_add_f32 v[78:79], v[78:79], 1.0 op_sel_hi:[1,0] neg_lo:[1,0] neg_hi:[1,0]
	v_pk_add_f32 v[72:73], v[72:73], 1.0 op_sel_hi:[1,0] neg_lo:[1,0] neg_hi:[1,0]
	v_pk_add_f32 v[68:69], v[68:69], 1.0 op_sel_hi:[1,0] neg_lo:[1,0] neg_hi:[1,0]
	v_pk_add_f32 v[64:65], v[64:65], 1.0 op_sel_hi:[1,0] neg_lo:[1,0] neg_hi:[1,0]
	v_pk_mul_f32 v[74:75], v[78:79], v[74:75]
	v_pk_mul_f32 v[70:71], v[72:73], v[70:71]
	v_pk_mul_f32 v[66:67], v[68:69], v[66:67]
	v_pk_mul_f32 v[62:63], v[64:65], v[62:63]
	v_pk_add_f32 v[60:61], v[60:61], 1.0 op_sel_hi:[1,0] neg_lo:[1,0] neg_hi:[1,0]
	v_pk_add_f32 v[56:57], v[56:57], 1.0 op_sel_hi:[1,0] neg_lo:[1,0] neg_hi:[1,0]
	v_pk_add_f32 v[52:53], v[52:53], 1.0 op_sel_hi:[1,0] neg_lo:[1,0] neg_hi:[1,0]
	v_pk_add_f32 v[12:13], v[12:13], 1.0 op_sel_hi:[1,0] neg_lo:[1,0] neg_hi:[1,0]
	v_cvt_pk_bf16_f32 v74, v74, v75
	v_add3_u32 v11, v11, v88, v84
	v_cvt_pk_bf16_f32 v70, v70, v71
	v_cvt_pk_bf16_f32 v66, v66, v67
	v_cvt_pk_bf16_f32 v62, v62, v63
	v_pk_mul_f32 v[58:59], v[60:61], v[58:59]
	v_pk_mul_f32 v[54:55], v[56:57], v[54:55]
	v_pk_mul_f32 v[16:17], v[52:53], v[16:17]
	v_pk_mul_f32 v[12:13], v[12:13], v[14:15]
	ds_write2_b32 v11, v74, v70 offset1:72
	ds_write2_b32 v11, v66, v62 offset0:144 offset1:216
	v_cvt_pk_bf16_f32 v58, v58, v59
	v_cvt_pk_bf16_f32 v54, v54, v55
	v_add_u32_e32 v11, 0x400, v11
	v_cvt_pk_bf16_f32 v16, v16, v17
	s_mov_b32 s16, 0x3fb8aa3b
	v_cvt_pk_bf16_f32 v12, v12, v13
	ds_write2_b32 v11, v58, v54 offset0:32 offset1:104
	ds_write2_b32 v11, v16, v12 offset0:176 offset1:248
	s_and_saveexec_b64 s[4:5], s[36:37]
	s_cbranch_execz .LBB0_335
	v_pk_mul_f32 v[12:13], v[76:77], s[16:17] op_sel_hi:[1,0]
	v_lshl_add_u64 v[14:15], s[80:81], 0, v[48:49]
	v_exp_f32_e32 v12, v12
	v_exp_f32_e32 v13, v13
	global_store_dwordx2 v[14:15], v[12:13], off
